# v30: v29 + loop control and next-iteration pointer selects moved into the middle of the last segment's MFMA block (MFMA shadow) instead of the loop head, both input-projection GEMM loops
# baseline (speedup 1.0000x reference)
.Lb1_ph3:
	s_add_i32 s50, 16, 0x18000
	v_add_u32_e32 v151, s50, v176
	s_add_i32 s51, 16, 0x1c000
	ds_read_b128 v[132:135], v151
	ds_read_b128 v[152:155], v151 offset:1024
	ds_read_b128 v[156:159], v151 offset:2048
	ds_read_b128 v[160:163], v151 offset:3072
	v_add_u32_e32 v151, s51, v176
	ds_read_b128 v[164:167], v151
	ds_read_b128 v[168:171], v151 offset:1024
	ds_read_b128 v[172:175], v151 offset:2048
	ds_read_b128 v[180:183], v151 offset:3072
	s_mov_b32 m0, s37
	s_nop 0
	global_load_lds_dwordx4 v[220:221], off
	s_mov_b32 m0, s38
	s_nop 0
	global_load_lds_dwordx4 v[224:225], off
	s_add_u32 s8, s8, 0x40000
	s_addc_u32 s9, s9, 0
	s_mov_b32 m0, s39
	v_lshl_add_u64 v[226:227], s[8:9], 0, v[140:141]
	ds_read_b128 v[184:187], v178 offset:32768
	ds_read_b128 v[188:191], v178 offset:33792
	ds_read_b128 v[192:195], v178 offset:34816
	ds_read_b128 v[196:199], v178 offset:35840
	ds_read_b128 v[200:203], v178 offset:36864
	ds_read_b128 v[204:207], v178 offset:37888
	ds_read_b128 v[208:211], v178 offset:38912
	ds_read_b128 v[212:215], v178 offset:39936
	global_load_lds_dwordx4 v[226:227], off
	v_lshl_add_u64 v[226:227], s[8:9], 0, v[136:137]
	s_mov_b32 m0, s40
	s_nop 0
	global_load_lds_dwordx4 v[226:227], off
	s_waitcnt vmcnt(8)
	s_waitcnt lgkmcnt(0)
	s_barrier
	s_setprio 1
	s_waitcnt lgkmcnt(0)
	v_mfma_f32_16x16x32_bf16 v[128:131], v[132:135], v[184:187], v[128:131]
	v_mfma_f32_16x16x32_bf16 v[124:127], v[156:159], v[184:187], v[124:127]
	v_mfma_f32_16x16x32_bf16 v[112:115], v[132:135], v[192:195], v[112:115]
	v_mfma_f32_16x16x32_bf16 v[108:111], v[156:159], v[192:195], v[108:111]
	v_mfma_f32_16x16x32_bf16 v[96:99], v[132:135], v[200:203], v[96:99]
	v_mfma_f32_16x16x32_bf16 v[92:95], v[156:159], v[200:203], v[92:95]
	v_mfma_f32_16x16x32_bf16 v[80:83], v[132:135], v[208:211], v[80:83]
	v_mfma_f32_16x16x32_bf16 v[76:79], v[156:159], v[208:211], v[76:79]
	v_mfma_f32_16x16x32_bf16 v[128:131], v[152:155], v[188:191], v[128:131]
	v_mfma_f32_16x16x32_bf16 v[124:127], v[160:163], v[188:191], v[124:127]
	v_mfma_f32_16x16x32_bf16 v[112:115], v[152:155], v[196:199], v[112:115]
	v_mfma_f32_16x16x32_bf16 v[108:111], v[160:163], v[196:199], v[108:111]
	v_mfma_f32_16x16x32_bf16 v[96:99], v[152:155], v[204:207], v[96:99]
	v_mfma_f32_16x16x32_bf16 v[92:95], v[160:163], v[204:207], v[92:95]
	v_mfma_f32_16x16x32_bf16 v[80:83], v[152:155], v[212:215], v[80:83]
	v_mfma_f32_16x16x32_bf16 v[76:79], v[160:163], v[212:215], v[76:79]
	s_setprio 0
	s_setprio 1
	v_mfma_f32_16x16x32_bf16 v[120:123], v[164:167], v[184:187], v[120:123]
	v_mfma_f32_16x16x32_bf16 v[116:119], v[172:175], v[184:187], v[116:119]
	v_mfma_f32_16x16x32_bf16 v[104:107], v[164:167], v[192:195], v[104:107]
	v_mfma_f32_16x16x32_bf16 v[100:103], v[172:175], v[192:195], v[100:103]
	v_mfma_f32_16x16x32_bf16 v[88:91], v[164:167], v[200:203], v[88:91]
	v_mfma_f32_16x16x32_bf16 v[84:87], v[172:175], v[200:203], v[84:87]
	v_mfma_f32_16x16x32_bf16 v[72:75], v[164:167], v[208:211], v[72:75]
	v_mfma_f32_16x16x32_bf16 v[68:71], v[172:175], v[208:211], v[68:71]
	v_mfma_f32_16x16x32_bf16 v[120:123], v[168:171], v[188:191], v[120:123]
	v_mfma_f32_16x16x32_bf16 v[116:119], v[180:183], v[188:191], v[116:119]
	v_mfma_f32_16x16x32_bf16 v[104:107], v[168:171], v[196:199], v[104:107]
	v_mfma_f32_16x16x32_bf16 v[100:103], v[180:183], v[196:199], v[100:103]
	v_mfma_f32_16x16x32_bf16 v[88:91], v[168:171], v[204:207], v[88:91]
	v_mfma_f32_16x16x32_bf16 v[84:87], v[180:183], v[204:207], v[84:87]
	v_mfma_f32_16x16x32_bf16 v[72:75], v[168:171], v[212:215], v[72:75]
	v_mfma_f32_16x16x32_bf16 v[68:71], v[180:183], v[212:215], v[68:71]
	s_setprio 0
	s_barrier
	s_add_i32 s8, s50, s36
	v_lshl_add_u64 v[216:217], v[216:217], 0, s[84:85]
	s_mov_b32 m0, s8
	ds_read_b128 v[184:187], v178 offset:49152
	ds_read_b128 v[188:191], v178 offset:50176
	ds_read_b128 v[192:195], v178 offset:51200
	ds_read_b128 v[196:199], v178 offset:52224
	ds_read_b128 v[200:203], v178 offset:53248
	ds_read_b128 v[204:207], v178 offset:54272
	ds_read_b128 v[208:211], v178 offset:55296
	ds_read_b128 v[212:215], v178 offset:56320
	global_load_lds_dwordx4 v[216:217], off
	s_add_i32 m0, s8, 0x2000
	s_add_u32 s6, s6, 0x40080
	v_lshl_add_u64 v[216:217], v[218:219], 0, s[84:85]
	s_addc_u32 s7, s7, 0
	s_add_i32 s8, s51, s36
	global_load_lds_dwordx4 v[216:217], off
	v_lshl_add_u64 v[216:217], s[6:7], 0, v[138:139]
	s_mov_b32 m0, s8
	s_nop 0
	global_load_lds_dwordx4 v[216:217], off
	v_lshl_add_u64 v[216:217], s[6:7], 0, v[0:1]
	s_add_i32 m0, s8, 0x2000
	s_nop 0
	global_load_lds_dwordx4 v[216:217], off
	v_lshl_add_u64 v[216:217], v[220:221], 0, s[84:85]
	s_mov_b32 m0, s44
	s_nop 0
	global_load_lds_dwordx4 v[216:217], off
	v_lshl_add_u64 v[216:217], v[224:225], 0, s[84:85]
	s_mov_b32 m0, s45
	s_nop 0
	global_load_lds_dwordx4 v[216:217], off
	s_waitcnt vmcnt(8)
	s_waitcnt lgkmcnt(0)
	s_barrier
	s_setprio 1
	s_waitcnt lgkmcnt(0)
	v_mfma_f32_16x16x32_bf16 v[64:67], v[132:135], v[184:187], v[64:67]
	v_mfma_f32_16x16x32_bf16 v[60:63], v[156:159], v[184:187], v[60:63]
	v_mfma_f32_16x16x32_bf16 v[48:51], v[132:135], v[192:195], v[48:51]
	v_mfma_f32_16x16x32_bf16 v[44:47], v[156:159], v[192:195], v[44:47]
	v_mfma_f32_16x16x32_bf16 v[32:35], v[132:135], v[200:203], v[32:35]
	v_mfma_f32_16x16x32_bf16 v[28:31], v[156:159], v[200:203], v[28:31]
	v_mfma_f32_16x16x32_bf16 v[16:19], v[132:135], v[208:211], v[16:19]
	v_mfma_f32_16x16x32_bf16 v[12:15], v[156:159], v[208:211], v[12:15]
	v_mfma_f32_16x16x32_bf16 v[64:67], v[152:155], v[188:191], v[64:67]
	v_mfma_f32_16x16x32_bf16 v[60:63], v[160:163], v[188:191], v[60:63]
	v_mfma_f32_16x16x32_bf16 v[48:51], v[152:155], v[196:199], v[48:51]
	v_mfma_f32_16x16x32_bf16 v[44:47], v[160:163], v[196:199], v[44:47]
	v_mfma_f32_16x16x32_bf16 v[32:35], v[152:155], v[204:207], v[32:35]
	v_mfma_f32_16x16x32_bf16 v[28:31], v[160:163], v[204:207], v[28:31]
	v_mfma_f32_16x16x32_bf16 v[16:19], v[152:155], v[212:215], v[16:19]
	v_mfma_f32_16x16x32_bf16 v[12:15], v[160:163], v[212:215], v[12:15]
	s_setprio 0
	s_add_i32 s49, s49, 2
	s_add_u32 s0, s0, 0x100
	s_addc_u32 s1, s1, 0
	s_add_u32 s29, s29, 0x100
	s_addc_u32 s42, s42, 0
	s_add_u32 s6, s0, 0xfffc0080
	s_addc_u32 s7, s1, -1
	s_cmp_eq_u32 s49, 12
	s_cselect_b32 s9, s3, s7
	s_cselect_b32 s8, s23, s6
	s_cselect_b32 s7, s21, s42
	s_cselect_b32 s6, s28, s29
	s_setprio 1
	v_mfma_f32_16x16x32_bf16 v[56:59], v[164:167], v[184:187], v[56:59]
	v_mfma_f32_16x16x32_bf16 v[52:55], v[172:175], v[184:187], v[52:55]
	v_mfma_f32_16x16x32_bf16 v[40:43], v[164:167], v[192:195], v[40:43]
	v_mfma_f32_16x16x32_bf16 v[36:39], v[172:175], v[192:195], v[36:39]
	v_mfma_f32_16x16x32_bf16 v[24:27], v[164:167], v[200:203], v[24:27]
	v_mfma_f32_16x16x32_bf16 v[20:23], v[172:175], v[200:203], v[20:23]
	v_mfma_f32_16x16x32_bf16 v[8:11], v[164:167], v[208:211], v[8:11]
	v_mfma_f32_16x16x32_bf16 v[4:7], v[172:175], v[208:211], v[4:7]
	v_mfma_f32_16x16x32_bf16 v[56:59], v[168:171], v[188:191], v[56:59]
	v_mfma_f32_16x16x32_bf16 v[52:55], v[180:183], v[188:191], v[52:55]
	v_mfma_f32_16x16x32_bf16 v[40:43], v[168:171], v[196:199], v[40:43]
	v_mfma_f32_16x16x32_bf16 v[36:39], v[180:183], v[196:199], v[36:39]
	v_mfma_f32_16x16x32_bf16 v[24:27], v[168:171], v[204:207], v[24:27]
	v_mfma_f32_16x16x32_bf16 v[20:23], v[180:183], v[204:207], v[20:23]
	v_mfma_f32_16x16x32_bf16 v[8:11], v[168:171], v[212:215], v[8:11]
	v_mfma_f32_16x16x32_bf16 v[4:7], v[180:183], v[212:215], v[4:7]
	s_setprio 0
	s_barrier
	s_cmp_gt_u32 s49, 13
	s_cbranch_scc0 .LBB0_156
	s_and_b64 vcc, exec, s[18:19]
	s_cbranch_vccz .LBB0_159
	s_barrier

.La1_ph3:
	s_add_i32 s52, 16, 0x18000
	v_add_u32_e32 v3, s52, v175
	s_add_i32 s53, 16, 0x1c000
	ds_read_b128 v[142:145], v3
	ds_read_b128 v[146:149], v3 offset:1024
	ds_read_b128 v[150:153], v3 offset:2048
	ds_read_b128 v[154:157], v3 offset:3072
	v_add_u32_e32 v3, s53, v175
	ds_read_b128 v[158:161], v3
	ds_read_b128 v[162:165], v3 offset:1024
	ds_read_b128 v[166:169], v3 offset:2048
	ds_read_b128 v[170:173], v3 offset:3072
	s_mov_b32 m0, s39
	s_nop 0
	global_load_lds_dwordx4 v[214:215], off
	s_mov_b32 m0, s40
	s_nop 0
	global_load_lds_dwordx4 v[216:217], off
	s_add_u32 s30, s30, 0x40000
	s_addc_u32 s31, s31, 0
	s_mov_b32 m0, s41
	v_lshl_add_u64 v[218:219], s[30:31], 0, v[136:137]
	ds_read_b128 v[178:181], v177 offset:32768
	ds_read_b128 v[182:185], v177 offset:33792
	ds_read_b128 v[186:189], v177 offset:34816
	ds_read_b128 v[190:193], v177 offset:35840
	ds_read_b128 v[194:197], v177 offset:36864
	ds_read_b128 v[198:201], v177 offset:37888
	ds_read_b128 v[202:205], v177 offset:38912
	ds_read_b128 v[206:209], v177 offset:39936
	global_load_lds_dwordx4 v[218:219], off
	v_lshl_add_u64 v[218:219], s[30:31], 0, v[132:133]
	s_mov_b32 m0, s42
	s_nop 0
	global_load_lds_dwordx4 v[218:219], off
	s_waitcnt vmcnt(8)
	s_waitcnt lgkmcnt(0)
	s_barrier
	s_setprio 1
	s_waitcnt lgkmcnt(0)
	v_mfma_f32_16x16x32_bf16 v[128:131], v[142:145], v[178:181], v[128:131]
	v_mfma_f32_16x16x32_bf16 v[120:123], v[150:153], v[178:181], v[120:123]
	v_mfma_f32_16x16x32_bf16 v[112:115], v[142:145], v[186:189], v[112:115]
	v_mfma_f32_16x16x32_bf16 v[104:107], v[150:153], v[186:189], v[104:107]
	v_mfma_f32_16x16x32_bf16 v[96:99], v[142:145], v[194:197], v[96:99]
	v_mfma_f32_16x16x32_bf16 v[88:91], v[150:153], v[194:197], v[88:91]
	v_mfma_f32_16x16x32_bf16 v[80:83], v[142:145], v[202:205], v[80:83]
	v_mfma_f32_16x16x32_bf16 v[72:75], v[150:153], v[202:205], v[72:75]
	v_mfma_f32_16x16x32_bf16 v[128:131], v[146:149], v[182:185], v[128:131]
	v_mfma_f32_16x16x32_bf16 v[120:123], v[154:157], v[182:185], v[120:123]
	v_mfma_f32_16x16x32_bf16 v[112:115], v[146:149], v[190:193], v[112:115]
	v_mfma_f32_16x16x32_bf16 v[104:107], v[154:157], v[190:193], v[104:107]
	v_mfma_f32_16x16x32_bf16 v[96:99], v[146:149], v[198:201], v[96:99]
	v_mfma_f32_16x16x32_bf16 v[88:91], v[154:157], v[198:201], v[88:91]
	v_mfma_f32_16x16x32_bf16 v[80:83], v[146:149], v[206:209], v[80:83]
	v_mfma_f32_16x16x32_bf16 v[72:75], v[154:157], v[206:209], v[72:75]
	s_setprio 0
	s_setprio 1
	v_mfma_f32_16x16x32_bf16 v[124:127], v[158:161], v[178:181], v[124:127]
	v_mfma_f32_16x16x32_bf16 v[116:119], v[166:169], v[178:181], v[116:119]
	v_mfma_f32_16x16x32_bf16 v[108:111], v[158:161], v[186:189], v[108:111]
	v_mfma_f32_16x16x32_bf16 v[100:103], v[166:169], v[186:189], v[100:103]
	v_mfma_f32_16x16x32_bf16 v[92:95], v[158:161], v[194:197], v[92:95]
	v_mfma_f32_16x16x32_bf16 v[84:87], v[166:169], v[194:197], v[84:87]
	v_mfma_f32_16x16x32_bf16 v[76:79], v[158:161], v[202:205], v[76:79]
	v_mfma_f32_16x16x32_bf16 v[68:71], v[166:169], v[202:205], v[68:71]
	v_mfma_f32_16x16x32_bf16 v[124:127], v[162:165], v[182:185], v[124:127]
	v_mfma_f32_16x16x32_bf16 v[116:119], v[170:173], v[182:185], v[116:119]
	v_mfma_f32_16x16x32_bf16 v[108:111], v[162:165], v[190:193], v[108:111]
	v_mfma_f32_16x16x32_bf16 v[100:103], v[170:173], v[190:193], v[100:103]
	v_mfma_f32_16x16x32_bf16 v[92:95], v[162:165], v[198:201], v[92:95]
	v_mfma_f32_16x16x32_bf16 v[84:87], v[170:173], v[198:201], v[84:87]
	v_mfma_f32_16x16x32_bf16 v[76:79], v[162:165], v[206:209], v[76:79]
	v_mfma_f32_16x16x32_bf16 v[68:71], v[170:173], v[206:209], v[68:71]
	s_setprio 0
	s_barrier
	s_add_i32 s30, s52, s38
	v_lshl_add_u64 v[210:211], v[210:211], 0, s[84:85]
	s_mov_b32 m0, s30
	ds_read_b128 v[178:181], v177 offset:49152
	ds_read_b128 v[182:185], v177 offset:50176
	ds_read_b128 v[186:189], v177 offset:51200
	ds_read_b128 v[190:193], v177 offset:52224
	ds_read_b128 v[194:197], v177 offset:53248
	ds_read_b128 v[198:201], v177 offset:54272
	ds_read_b128 v[202:205], v177 offset:55296
	ds_read_b128 v[206:209], v177 offset:56320
	global_load_lds_dwordx4 v[210:211], off
	s_add_i32 m0, s30, 0x2000
	s_add_u32 s28, s28, 0x40080
	v_lshl_add_u64 v[210:211], v[212:213], 0, s[84:85]
	s_addc_u32 s29, s29, 0
	s_add_i32 s30, s53, s38
	global_load_lds_dwordx4 v[210:211], off
	v_lshl_add_u64 v[210:211], s[28:29], 0, v[134:135]
	s_mov_b32 m0, s30
	s_nop 0
	global_load_lds_dwordx4 v[210:211], off
	v_lshl_add_u64 v[210:211], s[28:29], 0, v[0:1]
	s_add_i32 m0, s30, 0x2000
	s_nop 0
	global_load_lds_dwordx4 v[210:211], off
	v_lshl_add_u64 v[210:211], v[214:215], 0, s[84:85]
	s_mov_b32 m0, s44
	s_nop 0
	global_load_lds_dwordx4 v[210:211], off
	v_lshl_add_u64 v[210:211], v[216:217], 0, s[84:85]
	s_mov_b32 m0, s45
	s_nop 0
	global_load_lds_dwordx4 v[210:211], off
	s_waitcnt vmcnt(8)
	s_waitcnt lgkmcnt(0)
	s_barrier
	s_setprio 1
	s_waitcnt lgkmcnt(0)
	v_mfma_f32_16x16x32_bf16 v[64:67], v[142:145], v[178:181], v[64:67]
	v_mfma_f32_16x16x32_bf16 v[56:59], v[150:153], v[178:181], v[56:59]
	v_mfma_f32_16x16x32_bf16 v[48:51], v[142:145], v[186:189], v[48:51]
	v_mfma_f32_16x16x32_bf16 v[40:43], v[150:153], v[186:189], v[40:43]
	v_mfma_f32_16x16x32_bf16 v[32:35], v[142:145], v[194:197], v[32:35]
	v_mfma_f32_16x16x32_bf16 v[24:27], v[150:153], v[194:197], v[24:27]
	v_mfma_f32_16x16x32_bf16 v[16:19], v[142:145], v[202:205], v[16:19]
	v_mfma_f32_16x16x32_bf16 v[8:11], v[150:153], v[202:205], v[8:11]
	v_mfma_f32_16x16x32_bf16 v[64:67], v[146:149], v[182:185], v[64:67]
	v_mfma_f32_16x16x32_bf16 v[56:59], v[154:157], v[182:185], v[56:59]
	v_mfma_f32_16x16x32_bf16 v[48:51], v[146:149], v[190:193], v[48:51]
	v_mfma_f32_16x16x32_bf16 v[40:43], v[154:157], v[190:193], v[40:43]
	v_mfma_f32_16x16x32_bf16 v[32:35], v[146:149], v[198:201], v[32:35]
	v_mfma_f32_16x16x32_bf16 v[24:27], v[154:157], v[198:201], v[24:27]
	v_mfma_f32_16x16x32_bf16 v[16:19], v[146:149], v[206:209], v[16:19]
	v_mfma_f32_16x16x32_bf16 v[8:11], v[154:157], v[206:209], v[8:11]
	s_setprio 0
	s_add_i32 s51, s51, 2
	s_add_u32 s0, s0, 0x100
	s_addc_u32 s1, s1, 0
	s_add_u32 s49, s49, 0x100
	s_addc_u32 s50, s50, 0
	s_add_u32 s28, s0, 0xfffc0080
	s_addc_u32 s29, s1, -1
	s_cmp_eq_u32 s51, 12
	s_cselect_b32 s31, s3, s29
	s_cselect_b32 s30, s23, s28
	s_cselect_b32 s29, s21, s50
	s_cselect_b32 s28, s48, s49
	s_setprio 1
	v_mfma_f32_16x16x32_bf16 v[60:63], v[158:161], v[178:181], v[60:63]
	v_mfma_f32_16x16x32_bf16 v[52:55], v[166:169], v[178:181], v[52:55]
	v_mfma_f32_16x16x32_bf16 v[44:47], v[158:161], v[186:189], v[44:47]
	v_mfma_f32_16x16x32_bf16 v[36:39], v[166:169], v[186:189], v[36:39]
	v_mfma_f32_16x16x32_bf16 v[28:31], v[158:161], v[194:197], v[28:31]
	v_mfma_f32_16x16x32_bf16 v[20:23], v[166:169], v[194:197], v[20:23]
	v_mfma_f32_16x16x32_bf16 v[12:15], v[158:161], v[202:205], v[12:15]
	v_mfma_f32_16x16x32_bf16 v[4:7], v[166:169], v[202:205], v[4:7]
	v_mfma_f32_16x16x32_bf16 v[60:63], v[162:165], v[182:185], v[60:63]
	v_mfma_f32_16x16x32_bf16 v[52:55], v[170:173], v[182:185], v[52:55]
	v_mfma_f32_16x16x32_bf16 v[44:47], v[162:165], v[190:193], v[44:47]
	v_mfma_f32_16x16x32_bf16 v[36:39], v[170:173], v[190:193], v[36:39]
	v_mfma_f32_16x16x32_bf16 v[28:31], v[162:165], v[198:201], v[28:31]
	v_mfma_f32_16x16x32_bf16 v[20:23], v[170:173], v[198:201], v[20:23]
	v_mfma_f32_16x16x32_bf16 v[12:15], v[162:165], v[206:209], v[12:15]
	v_mfma_f32_16x16x32_bf16 v[4:7], v[170:173], v[206:209], v[4:7]
	s_setprio 0
	s_barrier
	s_cmp_gt_u32 s51, 13
	s_cbranch_scc0 .LBB0_446
	s_and_b64 vcc, exec, s[18:19]
	s_cbranch_vccz .LBB0_449
	s_barrier
